# v57 + up GEMM epilogue: 103 accumulator i32->f32 conversions moved in front of the first load wait (they cover the operand loads' round trip)
# baseline (speedup 1.0000x reference)
;     __device__ __forceinline__ void operator()(f32x4 (&acc)[2][2][4][2], const Unit& u, int wr, int wc, int fr_in, int fq_in, int wid, LAS unsigned char* lds) const {
;     ...
;         float sv[8]; u32x4 cv[4];
; #pragma unroll
;         for (int k = 0; k < 8; ++k) sv[k] = sa[rowg + (k >> 2) * HALF + (k & 3) * 16 + fr] * (1.0f / 127.0f);
; #pragma unroll
;         for (int k = 0; k < 4; ++k) cv[k] = *(const u32x4*)(cmax + colw + 8 * fq + (k >> 1) * CBJ + (k & 1) * 4);
; #pragma unroll
;         for (int ai = 0; ai < 2; ++ai)
; #pragma unroll
;             for (int m = 0; m < 4; ++m) {
;                 const float s = sv[ai * 4 + m];
;                 float mx = 0.f;
; #pragma unroll
;                 for (int bj = 0; bj < 2; ++bj) {
;                     const v4i_t i0 = __builtin_bit_cast(v4i_t, acc[ai][bj][m][0]), i1 = __builtin_bit_cast(v4i_t, acc[ai][bj][m][1]);
.LBB0_1339:
	s_mov_b32 s0, s81
	s_mov_b32 s1, -1
	s_lshl_b32 s40, s52, 8
	v_mov_b32_e32 v130, v162
	v_mov_b32_e32 v166, v163
	s_add_i32 s0, s40, s47
	v_readlane_b32 s42, v249, 57
	v_add_u32_e32 v114, s0, v130
	v_ashrrev_i32_e32 v115, 31, v114
	v_readlane_b32 s43, v249, 58
	s_lshl_b32 s1, s53, 8
	s_or_b32 s82, s1, s84
	v_lshl_add_u64 v[116:117], v[114:115], 2, s[42:43]
	global_load_dword v115, v[116:117], off
	v_add_u32_e32 v116, 16, v114
	v_ashrrev_i32_e32 v117, 31, v116
	v_lshl_add_u64 v[116:117], v[116:117], 2, s[42:43]
	global_load_dword v176, v[116:117], off
	v_add_u32_e32 v116, 32, v114
	v_ashrrev_i32_e32 v117, 31, v116
	v_lshl_add_u64 v[116:117], v[116:117], 2, s[42:43]
	global_load_dword v175, v[116:117], off
	v_add_u32_e32 v116, 48, v114
	v_ashrrev_i32_e32 v117, 31, v116
	v_lshl_add_u64 v[116:117], v[116:117], 2, s[42:43]
	global_load_dword v174, v[116:117], off
	v_add_u32_e32 v116, 0x80, v114
	v_ashrrev_i32_e32 v117, 31, v116
	v_lshl_add_u64 v[116:117], v[116:117], 2, s[42:43]
	global_load_dword v173, v[116:117], off
	v_add_u32_e32 v116, 0x90, v114
	v_ashrrev_i32_e32 v117, 31, v116
	v_lshl_add_u64 v[116:117], v[116:117], 2, s[42:43]
	global_load_dword v172, v[116:117], off
	v_add_u32_e32 v116, 0xa0, v114
	v_add_u32_e32 v114, 0xb0, v114
	v_ashrrev_i32_e32 v117, 31, v116
	s_ashr_i32 s83, s82, 31
	v_lshl_add_u64 v[116:117], v[116:117], 2, s[42:43]
	v_lshlrev_b32_e32 v160, 3, v166
	v_ashrrev_i32_e32 v161, 31, v160
	global_load_dword v171, v[116:117], off
	v_mov_b32_e32 v182, v114
	v_ashrrev_i32_e32 v183, 31, v114
	v_lshl_add_u64 v[182:183], v[182:183], 2, s[42:43]
	global_load_dword v167, v[182:183], off
	s_lshl_b64 s[98:99], s[82:83], 2
	s_add_u32 s98, s35, s98
	s_addc_u32 s99, s38, s99
	v_lshl_add_u64 v[184:185], v[160:161], 2, s[98:99]
	global_load_dwordx4 v[126:129], v[184:185], off offset:16
	global_load_dwordx4 v[136:139], v[184:185], off
	global_load_dwordx4 v[186:189], v[184:185], off offset:144
	global_load_dwordx4 v[190:193], v[184:185], off offset:128
	v_cvt_f32_i32_e32 v144, v144
	v_cvt_f32_i32_e32 v145, v145
	v_cvt_f32_i32_e32 v140, v140
	v_cvt_f32_i32_e32 v141, v141
	v_cvt_f32_i32_e32 v146, v146
	v_cvt_f32_i32_e32 v147, v147
	v_cvt_f32_i32_e32 v142, v142
	v_cvt_f32_i32_e32 v143, v143
	v_cvt_f32_i32_e32 v132, v132
	v_cvt_f32_i32_e32 v133, v133
	v_cvt_f32_i32_e32 v122, v122
	v_cvt_f32_i32_e32 v123, v123
	v_cvt_f32_i32_e32 v134, v134
	v_cvt_f32_i32_e32 v124, v124
	v_cvt_f32_i32_e32 v135, v135
	v_cvt_f32_i32_e32 v125, v125
	v_and_b32_e32 v169, 64, v204
	v_xor_b32_e32 v168, 16, v204
	v_add_u32_e32 v170, 64, v169
	v_cmp_lt_i32_e32 vcc, v168, v170
	v_cvt_f32_i32_e32 v110, v110
	v_cvt_f32_i32_e32 v111, v111
	v_cvt_f32_i32_e32 v106, v106
	v_cvt_f32_i32_e32 v107, v107
	v_cvt_f32_i32_e32 v112, v112
	v_cvt_f32_i32_e32 v113, v113
	v_cvt_f32_i32_e32 v108, v108
	v_cvt_f32_i32_e32 v109, v109
	v_cvt_f32_i32_e32 v102, v102
	v_cvt_f32_i32_e32 v103, v103
	v_cvt_f32_i32_e32 v98, v98
	v_cvt_f32_i32_e32 v99, v99
	v_cvt_f32_i32_e32 v104, v104
	v_cvt_f32_i32_e32 v100, v100
	v_cvt_f32_i32_e32 v105, v105
	v_cvt_f32_i32_e32 v101, v101
	v_cvt_f32_i32_e32 v94, v94
	v_cvt_f32_i32_e32 v95, v95
	v_cvt_f32_i32_e32 v90, v90
	v_cvt_f32_i32_e32 v91, v91
	v_cvt_f32_i32_e32 v96, v96
	v_cvt_f32_i32_e32 v97, v97
	v_cvt_f32_i32_e32 v92, v92
	v_cvt_f32_i32_e32 v93, v93
	v_cvt_f32_i32_e32 v86, v86
	v_cvt_f32_i32_e32 v87, v87
	v_cvt_f32_i32_e32 v82, v82
	v_cvt_f32_i32_e32 v83, v83
	v_cvt_f32_i32_e32 v88, v88
	v_cvt_f32_i32_e32 v84, v84
	v_cvt_f32_i32_e32 v89, v89
	v_cvt_f32_i32_e32 v85, v85
	v_cvt_f32_i32_e32 v78, v78
	v_cvt_f32_i32_e32 v79, v79
	v_cvt_f32_i32_e32 v74, v74
	v_cvt_f32_i32_e32 v75, v75
	v_cvt_f32_i32_e32 v80, v80
	v_cvt_f32_i32_e32 v81, v81
	v_cvt_f32_i32_e32 v76, v76
	v_cvt_f32_i32_e32 v77, v77
	v_cvt_f32_i32_e32 v70, v70
	v_cvt_f32_i32_e32 v71, v71
	v_cvt_f32_i32_e32 v66, v66
	v_cvt_f32_i32_e32 v67, v67
	v_cvt_f32_i32_e32 v72, v72
	v_cvt_f32_i32_e32 v68, v68
	v_cvt_f32_i32_e32 v73, v73
	v_cvt_f32_i32_e32 v69, v69
	v_cvt_f32_i32_e32 v62, v62
	v_cvt_f32_i32_e32 v63, v63
	v_cvt_f32_i32_e32 v58, v58
	v_cvt_f32_i32_e32 v59, v59
	v_cvt_f32_i32_e32 v64, v64
	v_cvt_f32_i32_e32 v65, v65
	v_cvt_f32_i32_e32 v60, v60
	v_cvt_f32_i32_e32 v61, v61
	v_cvt_f32_i32_e32 v54, v54
	v_cvt_f32_i32_e32 v55, v55
	v_cvt_f32_i32_e32 v50, v50
	v_cvt_f32_i32_e32 v51, v51
	v_cvt_f32_i32_e32 v56, v56
	v_cvt_f32_i32_e32 v52, v52
	v_cvt_f32_i32_e32 v57, v57
	v_cvt_f32_i32_e32 v53, v53
	v_cvt_f32_i32_e32 v46, v46
	v_cvt_f32_i32_e32 v47, v47
	v_cvt_f32_i32_e32 v42, v42
	v_cvt_f32_i32_e32 v43, v43
	v_cvt_f32_i32_e32 v48, v48
	v_cvt_f32_i32_e32 v49, v49
	v_cvt_f32_i32_e32 v44, v44
	v_cvt_f32_i32_e32 v45, v45
	v_cvt_f32_i32_e32 v38, v38
	v_cvt_f32_i32_e32 v39, v39
	v_cvt_f32_i32_e32 v34, v34
	v_cvt_f32_i32_e32 v35, v35
	v_cvt_f32_i32_e32 v40, v40
	v_cvt_f32_i32_e32 v36, v36
	v_cvt_f32_i32_e32 v41, v41
	v_cvt_f32_i32_e32 v37, v37
	v_cvt_f32_i32_e32 v30, v30
	v_cvt_f32_i32_e32 v31, v31
	v_cvt_f32_i32_e32 v26, v26
	v_cvt_f32_i32_e32 v27, v27
	v_cvt_f32_i32_e32 v32, v32
	v_cvt_f32_i32_e32 v33, v33
	v_cvt_f32_i32_e32 v28, v28
	v_cvt_f32_i32_e32 v29, v29
	v_cvt_f32_i32_e32 v22, v22
	v_cvt_f32_i32_e32 v18, v18
	v_cvt_f32_i32_e32 v19, v19
	v_cvt_f32_i32_e32 v20, v20
	v_cvt_f32_i32_e32 v21, v21
	v_cvt_f32_i32_e32 v14, v14
	v_cvt_f32_i32_e32 v10, v10
	v_cvt_f32_i32_e32 v11, v11
	v_cvt_f32_i32_e32 v12, v12
	v_cvt_f32_i32_e32 v13, v13
	v_cvt_f32_i32_e32 v6, v6
	v_cvt_f32_i32_e32 v2, v2
	v_cvt_f32_i32_e32 v3, v3
	v_cvt_f32_i32_e32 v4, v4
	v_cvt_f32_i32_e32 v5, v5
	s_waitcnt vmcnt(5)
;     __device__ __forceinline__ void operator()(f32x4 (&acc)[2][2][4][2], const Unit& u, int wr, int wc, int fr_in, int fq_in, int wid, LAS unsigned char* lds) const {
;     ...
;         for (int ai = 0; ai < 2; ++ai)
; #pragma unroll
;             for (int m = 0; m < 4; ++m) {
;                 const float s = sv[ai * 4 + m];
;                 float mx = 0.f;
; #pragma unroll
;                 for (int bj = 0; bj < 2; ++bj) {
;                     const v4i_t i0 = __builtin_bit_cast(v4i_t, acc[ai][bj][m][0]), i1 = __builtin_bit_cast(v4i_t, acc[ai][bj][m][1]);
;                     const u32x4 c0_ = cv[bj * 2], c1_ = cv[bj * 2 + 1];
;                     f32x4 v0, v1;
; #pragma unroll
;                     for (int j = 0; j < 4; ++j) { const float a = fmaxf((float)i0[j] * (s * __uint_as_float(c0_[j])), 0.f), b = fmaxf((float)i1[j] * (s * __uint_as_float(c1_[j])), 0.f); v0[j] = a * a; v1[j] = b * b; mx = fmaxf(mx, fmaxf(v0[j], v1[j])); }
;                     acc[ai][bj][m][0] = v0; acc[ai][bj][m][1] = v1;
;                 }
;                 mx = fmaxf(mx, __shfl_xor(mx, 16)); mx = fmaxf(mx, __shfl_xor(mx, 32));
;                 if (fq == 0) lmx[wc * 256 + wr * 64 + ai * HALF + m * 16 + fr] = mx;
	v_mul_f32_e32 v177, 0x3c010204, v115
	v_ashrrev_i32_e32 v115, 31, v114
	v_lshl_add_u64 v[114:115], v[114:115], 2, s[42:43]
	s_lshl_b64 s[42:43], s[82:83], 2
	s_add_u32 s42, s35, s42
	s_addc_u32 s43, s38, s43
	v_lshl_add_u64 v[118:119], v[160:161], 2, s[42:43]
	s_nop 0
	s_nop 0
	v_cndmask_b32_e32 v168, v204, v168, vcc
	v_lshlrev_b32_e32 v169, 2, v168
	v_xor_b32_e32 v168, 32, v204
	v_cmp_lt_i32_e32 vcc, v168, v170
	s_waitcnt vmcnt(2)
	v_mul_f32_e32 v178, v177, v136
	v_mul_f32_e32 v179, v177, v137
	v_mul_f32_e32 v144, v178, v144
	v_mul_f32_e32 v178, v177, v126
	v_mul_f32_e32 v145, v179, v145
	v_mul_f32_e32 v179, v177, v127
	v_mul_f32_e32 v140, v178, v140
	v_mul_f32_e32 v141, v179, v141
	v_max_f32_e32 v144, 0, v144
	v_max_f32_e32 v140, 0, v140
	v_max_f32_e32 v145, 0, v145
	v_max_f32_e32 v141, 0, v141
	v_mul_f32_e32 v144, v144, v144
	v_mul_f32_e32 v140, v140, v140
	v_mul_f32_e32 v145, v145, v145
	v_mul_f32_e32 v141, v141, v141
	v_max_f32_e32 v178, v144, v140
	v_max_f32_e32 v179, v145, v141
	v_max3_f32 v178, v178, 0, v179
	v_mul_f32_e32 v179, v177, v138
	v_mul_f32_e32 v180, v177, v139
	v_mul_f32_e32 v146, v179, v146
	v_mul_f32_e32 v179, v177, v128
	v_mul_f32_e32 v147, v180, v147
	v_mul_f32_e32 v180, v177, v129
	v_mul_f32_e32 v142, v179, v142
	v_mul_f32_e32 v143, v180, v143
	v_max_f32_e32 v146, 0, v146
	v_max_f32_e32 v142, 0, v142
	v_max_f32_e32 v147, 0, v147
	v_max_f32_e32 v143, 0, v143
	v_mul_f32_e32 v146, v146, v146
	v_mul_f32_e32 v142, v142, v142
	v_mul_f32_e32 v147, v147, v147
	v_mul_f32_e32 v143, v143, v143
	v_max_f32_e32 v179, v146, v142
	v_max_f32_e32 v180, v147, v143
	v_max3_f32 v178, v178, v179, v180
	s_waitcnt vmcnt(0)
	v_mov_b32_e32 v114, v186
	v_mov_b32_e32 v115, v187
	v_mov_b32_e32 v116, v188
	v_mov_b32_e32 v117, v189
	v_mov_b32_e32 v118, v190
	v_mov_b32_e32 v119, v191
	v_mov_b32_e32 v120, v192
	v_mov_b32_e32 v121, v193
	v_mul_f32_e32 v179, v177, v118
	v_mul_f32_e32 v180, v177, v119
	v_mul_f32_e32 v132, v179, v132
	v_mul_f32_e32 v179, v177, v114
	v_mul_f32_e32 v133, v180, v133
	v_mul_f32_e32 v180, v177, v115
	v_mul_f32_e32 v122, v179, v122
	v_mul_f32_e32 v123, v180, v123
	v_max_f32_e32 v132, 0, v132
	v_max_f32_e32 v122, 0, v122
	v_max_f32_e32 v133, 0, v133
	v_max_f32_e32 v123, 0, v123
	v_mul_f32_e32 v132, v132, v132
	v_mul_f32_e32 v122, v122, v122
	v_mul_f32_e32 v133, v133, v133
	v_mul_f32_e32 v123, v123, v123
	v_max_f32_e32 v179, v132, v122
	v_max_f32_e32 v180, v133, v123
	v_max3_f32 v178, v178, v179, v180
	v_mul_f32_e32 v179, v177, v120
	v_mul_f32_e32 v134, v179, v134
	v_mul_f32_e32 v179, v177, v116
	v_mul_f32_e32 v180, v177, v121
	v_mul_f32_e32 v177, v177, v117
	v_mul_f32_e32 v124, v179, v124
	v_mul_f32_e32 v135, v180, v135
	v_mul_f32_e32 v125, v177, v125
	v_max_f32_e32 v134, 0, v134
	v_max_f32_e32 v124, 0, v124
	v_max_f32_e32 v135, 0, v135
	v_max_f32_e32 v125, 0, v125
	v_mul_f32_e32 v134, v134, v134
	v_mul_f32_e32 v124, v124, v124
	v_mul_f32_e32 v135, v135, v135
	v_mul_f32_e32 v125, v125, v125
	v_max_f32_e32 v179, v134, v124
	v_max_f32_e32 v177, v135, v125
	v_max3_f32 v177, v178, v179, v177
	ds_bpermute_b32 v178, v169, v177
	v_cndmask_b32_e32 v168, v204, v168, vcc
	v_lshlrev_b32_e32 v170, 2, v168
	v_cmp_eq_u32_e32 vcc, 0, v166
	v_lshl_add_u32 v168, v130, 2, s85
	s_waitcnt lgkmcnt(0)
	v_max_f32_e32 v178, v178, v178
	v_max_f32_e32 v177, v177, v178
	ds_bpermute_b32 v178, v170, v177
	s_and_saveexec_b64 s[42:43], vcc
	s_cbranch_execz .LBB0_1341
	s_waitcnt lgkmcnt(0)
	v_max_f32_e32 v178, v178, v178
	v_max_f32_e32 v177, v177, v177
	v_max_f32_e32 v177, v177, v178
	ds_write_b32 v168, v177
.LBB0_1341:
	s_or_b64 exec, exec, s[42:43]
	v_mul_f32_e32 v176, 0x3c010204, v176
	v_mul_f32_e32 v177, v176, v136
	s_waitcnt lgkmcnt(0)
	v_mul_f32_e32 v178, v176, v137
	v_mul_f32_e32 v110, v177, v110
	v_mul_f32_e32 v177, v176, v126
	v_mul_f32_e32 v111, v178, v111
	v_mul_f32_e32 v178, v176, v127
	v_mul_f32_e32 v106, v177, v106
	v_mul_f32_e32 v107, v178, v107
	v_max_f32_e32 v110, 0, v110
	v_max_f32_e32 v106, 0, v106
	v_max_f32_e32 v111, 0, v111
	v_max_f32_e32 v107, 0, v107
	v_mul_f32_e32 v110, v110, v110
	v_mul_f32_e32 v106, v106, v106
	v_mul_f32_e32 v111, v111, v111
	v_mul_f32_e32 v107, v107, v107
	v_max_f32_e32 v177, v110, v106
	v_max_f32_e32 v178, v111, v107
	v_max3_f32 v177, v177, 0, v178
	v_mul_f32_e32 v178, v176, v138
	v_mul_f32_e32 v179, v176, v139
	v_mul_f32_e32 v112, v178, v112
	v_mul_f32_e32 v178, v176, v128
	v_mul_f32_e32 v113, v179, v113
	v_mul_f32_e32 v179, v176, v129
	v_mul_f32_e32 v108, v178, v108
	v_mul_f32_e32 v109, v179, v109
	v_max_f32_e32 v112, 0, v112
	v_max_f32_e32 v108, 0, v108
	v_max_f32_e32 v113, 0, v113
	v_max_f32_e32 v109, 0, v109
	v_mul_f32_e32 v112, v112, v112
	v_mul_f32_e32 v108, v108, v108
	v_mul_f32_e32 v113, v113, v113
	v_mul_f32_e32 v109, v109, v109
	v_max_f32_e32 v178, v112, v108
	v_max_f32_e32 v179, v113, v109
	v_max3_f32 v177, v177, v178, v179
	v_mul_f32_e32 v178, v176, v118
	v_mul_f32_e32 v179, v176, v119
	v_mul_f32_e32 v102, v178, v102
	v_mul_f32_e32 v178, v176, v114
	v_mul_f32_e32 v103, v179, v103
	v_mul_f32_e32 v179, v176, v115
	v_mul_f32_e32 v98, v178, v98
	v_mul_f32_e32 v99, v179, v99
	v_max_f32_e32 v102, 0, v102
	v_max_f32_e32 v98, 0, v98
	v_max_f32_e32 v103, 0, v103
	v_max_f32_e32 v99, 0, v99
	v_mul_f32_e32 v102, v102, v102
	v_mul_f32_e32 v98, v98, v98
	v_mul_f32_e32 v103, v103, v103
	v_mul_f32_e32 v99, v99, v99
	v_max_f32_e32 v178, v102, v98
	v_max_f32_e32 v179, v103, v99
	v_max3_f32 v177, v177, v178, v179
	v_mul_f32_e32 v178, v176, v120
	v_mul_f32_e32 v104, v178, v104
	v_mul_f32_e32 v178, v176, v116
	v_mul_f32_e32 v179, v176, v121
	v_mul_f32_e32 v176, v176, v117
	v_mul_f32_e32 v100, v178, v100
	v_mul_f32_e32 v105, v179, v105
	v_mul_f32_e32 v101, v176, v101
	v_max_f32_e32 v104, 0, v104
	v_max_f32_e32 v100, 0, v100
	v_max_f32_e32 v105, 0, v105
	v_max_f32_e32 v101, 0, v101
	v_mul_f32_e32 v104, v104, v104
	v_mul_f32_e32 v100, v100, v100
	v_mul_f32_e32 v105, v105, v105
	v_mul_f32_e32 v101, v101, v101
	v_max_f32_e32 v178, v104, v100
	v_max_f32_e32 v176, v105, v101
	v_max3_f32 v176, v177, v178, v176
	ds_bpermute_b32 v177, v169, v176
	s_waitcnt lgkmcnt(0)
	v_max_f32_e32 v177, v177, v177
	v_max_f32_e32 v176, v176, v177
	ds_bpermute_b32 v177, v170, v176
	s_and_saveexec_b64 s[42:43], vcc
	s_cbranch_execz .LBB0_1343
	s_waitcnt lgkmcnt(0)
	v_max_f32_e32 v177, v177, v177
	v_max_f32_e32 v176, v176, v176
	v_max_f32_e32 v176, v176, v177
	ds_write_b32 v168, v176 offset:64
;     __device__ __forceinline__ void operator()(f32x4 (&acc)[2][2][4][2], const Unit& u, int wr, int wc, int fr_in, int fq_in, int wid, LAS unsigned char* lds) const {
;     ...
;         for (int ai = 0; ai < 2; ++ai)
; #pragma unroll
;             for (int m = 0; m < 4; ++m) {
;                 const float s = sv[ai * 4 + m];
;                 float mx = 0.f;
; #pragma unroll
;                 for (int bj = 0; bj < 2; ++bj) {
;                     const v4i_t i0 = __builtin_bit_cast(v4i_t, acc[ai][bj][m][0]), i1 = __builtin_bit_cast(v4i_t, acc[ai][bj][m][1]);
;                     const u32x4 c0_ = cv[bj * 2], c1_ = cv[bj * 2 + 1];
;                     f32x4 v0, v1;
; #pragma unroll
;                     for (int j = 0; j < 4; ++j) { const float a = fmaxf((float)i0[j] * (s * __uint_as_float(c0_[j])), 0.f), b = fmaxf((float)i1[j] * (s * __uint_as_float(c1_[j])), 0.f); v0[j] = a * a; v1[j] = b * b; mx = fmaxf(mx, fmaxf(v0[j], v1[j])); }
;                     acc[ai][bj][m][0] = v0; acc[ai][bj][m][1] = v1;
;                 }
;                 mx = fmaxf(mx, __shfl_xor(mx, 16)); mx = fmaxf(mx, __shfl_xor(mx, 32));
;                 if (fq == 0) lmx[wc * 256 + wr * 64 + ai * HALF + m * 16 + fr] = mx;
.LBB0_1343:
	s_or_b64 exec, exec, s[42:43]
	v_mul_f32_e32 v175, 0x3c010204, v175
	v_mul_f32_e32 v176, v175, v136
	s_waitcnt lgkmcnt(0)
	v_mul_f32_e32 v177, v175, v137
	v_mul_f32_e32 v94, v176, v94
	v_mul_f32_e32 v176, v175, v126
	v_mul_f32_e32 v95, v177, v95
	v_mul_f32_e32 v177, v175, v127
	v_mul_f32_e32 v90, v176, v90
	v_mul_f32_e32 v91, v177, v91
	v_max_f32_e32 v94, 0, v94
	v_max_f32_e32 v90, 0, v90
	v_max_f32_e32 v95, 0, v95
	v_max_f32_e32 v91, 0, v91
	v_mul_f32_e32 v94, v94, v94
	v_mul_f32_e32 v90, v90, v90
	v_mul_f32_e32 v95, v95, v95
	v_mul_f32_e32 v91, v91, v91
	v_max_f32_e32 v176, v94, v90
	v_max_f32_e32 v177, v95, v91
	v_max3_f32 v176, v176, 0, v177
	v_mul_f32_e32 v177, v175, v138
	v_mul_f32_e32 v178, v175, v139
	v_mul_f32_e32 v96, v177, v96
	v_mul_f32_e32 v177, v175, v128
	v_mul_f32_e32 v97, v178, v97
	v_mul_f32_e32 v178, v175, v129
	v_mul_f32_e32 v92, v177, v92
	v_mul_f32_e32 v93, v178, v93
	v_max_f32_e32 v96, 0, v96
	v_max_f32_e32 v92, 0, v92
	v_max_f32_e32 v97, 0, v97
	v_max_f32_e32 v93, 0, v93
	v_mul_f32_e32 v96, v96, v96
	v_mul_f32_e32 v92, v92, v92
	v_mul_f32_e32 v97, v97, v97
	v_mul_f32_e32 v93, v93, v93
	v_max_f32_e32 v177, v96, v92
	v_max_f32_e32 v178, v97, v93
	v_max3_f32 v176, v176, v177, v178
	v_mul_f32_e32 v177, v175, v118
	v_mul_f32_e32 v178, v175, v119
	v_mul_f32_e32 v86, v177, v86
	v_mul_f32_e32 v177, v175, v114
	v_mul_f32_e32 v87, v178, v87
	v_mul_f32_e32 v178, v175, v115
	v_mul_f32_e32 v82, v177, v82
	v_mul_f32_e32 v83, v178, v83
	v_max_f32_e32 v86, 0, v86
	v_max_f32_e32 v82, 0, v82
	v_max_f32_e32 v87, 0, v87
	v_max_f32_e32 v83, 0, v83
	v_mul_f32_e32 v86, v86, v86
	v_mul_f32_e32 v82, v82, v82
	v_mul_f32_e32 v87, v87, v87
	v_mul_f32_e32 v83, v83, v83
	v_max_f32_e32 v177, v86, v82
	v_max_f32_e32 v178, v87, v83
	v_max3_f32 v176, v176, v177, v178
	v_mul_f32_e32 v177, v175, v120
	v_mul_f32_e32 v88, v177, v88
	v_mul_f32_e32 v177, v175, v116
	v_mul_f32_e32 v178, v175, v121
	v_mul_f32_e32 v175, v175, v117
	v_mul_f32_e32 v84, v177, v84
	v_mul_f32_e32 v89, v178, v89
	v_mul_f32_e32 v85, v175, v85
	v_max_f32_e32 v88, 0, v88
	v_max_f32_e32 v84, 0, v84
	v_max_f32_e32 v89, 0, v89
	v_max_f32_e32 v85, 0, v85
	v_mul_f32_e32 v88, v88, v88
	v_mul_f32_e32 v84, v84, v84
	v_mul_f32_e32 v89, v89, v89
	v_mul_f32_e32 v85, v85, v85
	v_max_f32_e32 v177, v88, v84
	v_max_f32_e32 v175, v89, v85
	v_max3_f32 v175, v176, v177, v175
	ds_bpermute_b32 v176, v169, v175
	s_waitcnt lgkmcnt(0)
	v_max_f32_e32 v176, v176, v176
	v_max_f32_e32 v175, v175, v176
	ds_bpermute_b32 v176, v170, v175
	s_and_saveexec_b64 s[42:43], vcc
	v_readlane_b32 s94, v255, 38
	s_cbranch_execz .LBB0_1345
	s_waitcnt lgkmcnt(0)
	v_max_f32_e32 v176, v176, v176
	v_max_f32_e32 v175, v175, v175
	v_max_f32_e32 v175, v175, v176
	ds_write_b32 v168, v175 offset:128
.LBB0_1345:
	s_or_b64 exec, exec, s[42:43]
	v_mul_f32_e32 v174, 0x3c010204, v174
	v_mul_f32_e32 v175, v174, v136
	s_waitcnt lgkmcnt(0)
	v_mul_f32_e32 v176, v174, v137
	v_mul_f32_e32 v78, v175, v78
	v_mul_f32_e32 v175, v174, v126
	v_mul_f32_e32 v79, v176, v79
	v_mul_f32_e32 v176, v174, v127
	v_mul_f32_e32 v74, v175, v74
	v_mul_f32_e32 v75, v176, v75
	v_max_f32_e32 v78, 0, v78
	v_max_f32_e32 v74, 0, v74
	v_max_f32_e32 v79, 0, v79
	v_max_f32_e32 v75, 0, v75
	v_mul_f32_e32 v78, v78, v78
	v_mul_f32_e32 v74, v74, v74
	v_mul_f32_e32 v79, v79, v79
	v_mul_f32_e32 v75, v75, v75
	v_max_f32_e32 v175, v78, v74
	v_max_f32_e32 v176, v79, v75
	v_max3_f32 v175, v175, 0, v176
	v_mul_f32_e32 v176, v174, v138
	v_mul_f32_e32 v177, v174, v139
	v_mul_f32_e32 v80, v176, v80
	v_mul_f32_e32 v176, v174, v128
	v_mul_f32_e32 v81, v177, v81
	v_mul_f32_e32 v177, v174, v129
	v_mul_f32_e32 v76, v176, v76
	v_mul_f32_e32 v77, v177, v77
	v_max_f32_e32 v80, 0, v80
	v_max_f32_e32 v76, 0, v76
	v_max_f32_e32 v81, 0, v81
	v_max_f32_e32 v77, 0, v77
	v_mul_f32_e32 v80, v80, v80
	v_mul_f32_e32 v76, v76, v76
	v_mul_f32_e32 v81, v81, v81
	v_mul_f32_e32 v77, v77, v77
	v_max_f32_e32 v176, v80, v76
	v_max_f32_e32 v177, v81, v77
	v_max3_f32 v175, v175, v176, v177
	v_mul_f32_e32 v176, v174, v118
	v_mul_f32_e32 v177, v174, v119
	v_mul_f32_e32 v70, v176, v70
	v_mul_f32_e32 v176, v174, v114
	v_mul_f32_e32 v71, v177, v71
	v_mul_f32_e32 v177, v174, v115
	v_mul_f32_e32 v66, v176, v66
	v_mul_f32_e32 v67, v177, v67
	v_max_f32_e32 v70, 0, v70
	v_max_f32_e32 v66, 0, v66
	v_max_f32_e32 v71, 0, v71
	v_max_f32_e32 v67, 0, v67
	v_mul_f32_e32 v70, v70, v70
	v_mul_f32_e32 v66, v66, v66
	v_mul_f32_e32 v71, v71, v71
	v_mul_f32_e32 v67, v67, v67
	v_max_f32_e32 v176, v70, v66
	v_max_f32_e32 v177, v71, v67
	v_max3_f32 v175, v175, v176, v177
	v_mul_f32_e32 v176, v174, v120
	v_mul_f32_e32 v72, v176, v72
	v_mul_f32_e32 v176, v174, v116
	v_mul_f32_e32 v177, v174, v121
	v_mul_f32_e32 v174, v174, v117
	v_mul_f32_e32 v68, v176, v68
	v_mul_f32_e32 v73, v177, v73
	v_mul_f32_e32 v69, v174, v69
	v_max_f32_e32 v72, 0, v72
	v_max_f32_e32 v68, 0, v68
	v_max_f32_e32 v73, 0, v73
	v_max_f32_e32 v69, 0, v69
	v_mul_f32_e32 v72, v72, v72
	v_mul_f32_e32 v68, v68, v68
	v_mul_f32_e32 v73, v73, v73
	v_mul_f32_e32 v69, v69, v69
	v_max_f32_e32 v176, v72, v68
	v_max_f32_e32 v174, v73, v69
	v_max3_f32 v174, v175, v176, v174
	ds_bpermute_b32 v175, v169, v174
	s_waitcnt lgkmcnt(0)
	v_max_f32_e32 v175, v175, v175
	v_max_f32_e32 v174, v174, v175
	ds_bpermute_b32 v175, v170, v174
	s_and_saveexec_b64 s[42:43], vcc
	s_cbranch_execz .LBB0_1347
	s_waitcnt lgkmcnt(0)
	v_max_f32_e32 v175, v175, v175
	v_max_f32_e32 v174, v174, v174
	v_max_f32_e32 v174, v174, v175
	ds_write_b32 v168, v174 offset:192
;     __device__ __forceinline__ void operator()(f32x4 (&acc)[2][2][4][2], const Unit& u, int wr, int wc, int fr_in, int fq_in, int wid, LAS unsigned char* lds) const {
;     ...
;         for (int ai = 0; ai < 2; ++ai)
; #pragma unroll
;             for (int m = 0; m < 4; ++m) {
;                 const float s = sv[ai * 4 + m];
;                 float mx = 0.f;
; #pragma unroll
;                 for (int bj = 0; bj < 2; ++bj) {
;                     const v4i_t i0 = __builtin_bit_cast(v4i_t, acc[ai][bj][m][0]), i1 = __builtin_bit_cast(v4i_t, acc[ai][bj][m][1]);
;                     const u32x4 c0_ = cv[bj * 2], c1_ = cv[bj * 2 + 1];
;                     f32x4 v0, v1;
; #pragma unroll
;                     for (int j = 0; j < 4; ++j) { const float a = fmaxf((float)i0[j] * (s * __uint_as_float(c0_[j])), 0.f), b = fmaxf((float)i1[j] * (s * __uint_as_float(c1_[j])), 0.f); v0[j] = a * a; v1[j] = b * b; mx = fmaxf(mx, fmaxf(v0[j], v1[j])); }
;                     acc[ai][bj][m][0] = v0; acc[ai][bj][m][1] = v1;
;                 }
;                 mx = fmaxf(mx, __shfl_xor(mx, 16)); mx = fmaxf(mx, __shfl_xor(mx, 32));
;                 if (fq == 0) lmx[wc * 256 + wr * 64 + ai * HALF + m * 16 + fr] = mx;
.LBB0_1347:
	s_or_b64 exec, exec, s[42:43]
	v_mul_f32_e32 v173, 0x3c010204, v173
	v_mul_f32_e32 v174, v173, v136
	s_waitcnt lgkmcnt(0)
	v_mul_f32_e32 v175, v173, v137
	v_mul_f32_e32 v62, v174, v62
	v_mul_f32_e32 v174, v173, v126
	v_mul_f32_e32 v63, v175, v63
	v_mul_f32_e32 v175, v173, v127
	v_mul_f32_e32 v58, v174, v58
	v_mul_f32_e32 v59, v175, v59
	v_max_f32_e32 v62, 0, v62
	v_max_f32_e32 v58, 0, v58
	v_max_f32_e32 v63, 0, v63
	v_max_f32_e32 v59, 0, v59
	v_mul_f32_e32 v62, v62, v62
	v_mul_f32_e32 v58, v58, v58
	v_mul_f32_e32 v63, v63, v63
	v_mul_f32_e32 v59, v59, v59
	v_max_f32_e32 v174, v62, v58
	v_max_f32_e32 v175, v63, v59
	v_max3_f32 v174, v174, 0, v175
	v_mul_f32_e32 v175, v173, v138
	v_mul_f32_e32 v176, v173, v139
	v_mul_f32_e32 v64, v175, v64
	v_mul_f32_e32 v175, v173, v128
	v_mul_f32_e32 v65, v176, v65
	v_mul_f32_e32 v176, v173, v129
	v_mul_f32_e32 v60, v175, v60
	v_mul_f32_e32 v61, v176, v61
	v_max_f32_e32 v64, 0, v64
	v_max_f32_e32 v60, 0, v60
	v_max_f32_e32 v65, 0, v65
	v_max_f32_e32 v61, 0, v61
	v_mul_f32_e32 v64, v64, v64
	v_mul_f32_e32 v60, v60, v60
	v_mul_f32_e32 v65, v65, v65
	v_mul_f32_e32 v61, v61, v61
	v_max_f32_e32 v175, v64, v60
	v_max_f32_e32 v176, v65, v61
	v_max3_f32 v174, v174, v175, v176
	v_mul_f32_e32 v175, v173, v118
	v_mul_f32_e32 v176, v173, v119
	v_mul_f32_e32 v54, v175, v54
	v_mul_f32_e32 v175, v173, v114
	v_mul_f32_e32 v55, v176, v55
	v_mul_f32_e32 v176, v173, v115
	v_mul_f32_e32 v50, v175, v50
	v_mul_f32_e32 v51, v176, v51
	v_max_f32_e32 v54, 0, v54
	v_max_f32_e32 v50, 0, v50
	v_max_f32_e32 v55, 0, v55
	v_max_f32_e32 v51, 0, v51
	v_mul_f32_e32 v54, v54, v54
	v_mul_f32_e32 v50, v50, v50
	v_mul_f32_e32 v55, v55, v55
	v_mul_f32_e32 v51, v51, v51
	v_max_f32_e32 v175, v54, v50
	v_max_f32_e32 v176, v55, v51
	v_max3_f32 v174, v174, v175, v176
	v_mul_f32_e32 v175, v173, v120
	v_mul_f32_e32 v56, v175, v56
	v_mul_f32_e32 v175, v173, v116
	v_mul_f32_e32 v176, v173, v121
	v_mul_f32_e32 v173, v173, v117
	v_mul_f32_e32 v52, v175, v52
	v_mul_f32_e32 v57, v176, v57
	v_mul_f32_e32 v53, v173, v53
	v_max_f32_e32 v56, 0, v56
	v_max_f32_e32 v52, 0, v52
	v_max_f32_e32 v57, 0, v57
	v_max_f32_e32 v53, 0, v53
	v_mul_f32_e32 v56, v56, v56
	v_mul_f32_e32 v52, v52, v52
	v_mul_f32_e32 v57, v57, v57
	v_mul_f32_e32 v53, v53, v53
	v_max_f32_e32 v175, v56, v52
	v_max_f32_e32 v173, v57, v53
	v_max3_f32 v173, v174, v175, v173
	ds_bpermute_b32 v174, v169, v173
	s_waitcnt lgkmcnt(0)
	v_max_f32_e32 v174, v174, v174
	v_max_f32_e32 v173, v173, v174
	ds_bpermute_b32 v174, v170, v173
	s_and_saveexec_b64 s[42:43], vcc
	s_cbranch_execz .LBB0_1349
	s_waitcnt lgkmcnt(0)
	v_max_f32_e32 v174, v174, v174
	v_max_f32_e32 v173, v173, v173
	v_max_f32_e32 v173, v173, v174
	ds_write_b32 v168, v173 offset:512
.LBB0_1349:
	s_or_b64 exec, exec, s[42:43]
	v_mul_f32_e32 v172, 0x3c010204, v172
	v_mul_f32_e32 v173, v172, v136
	s_waitcnt lgkmcnt(0)
	v_mul_f32_e32 v174, v172, v137
	v_mul_f32_e32 v46, v173, v46
	v_mul_f32_e32 v173, v172, v126
	v_mul_f32_e32 v47, v174, v47
	v_mul_f32_e32 v174, v172, v127
	v_mul_f32_e32 v42, v173, v42
	v_mul_f32_e32 v43, v174, v43
	v_max_f32_e32 v46, 0, v46
	v_max_f32_e32 v42, 0, v42
	v_max_f32_e32 v47, 0, v47
	v_max_f32_e32 v43, 0, v43
	v_mul_f32_e32 v46, v46, v46
	v_mul_f32_e32 v42, v42, v42
	v_mul_f32_e32 v47, v47, v47
	v_mul_f32_e32 v43, v43, v43
	v_max_f32_e32 v173, v46, v42
	v_max_f32_e32 v174, v47, v43
	v_max3_f32 v173, v173, 0, v174
	v_mul_f32_e32 v174, v172, v138
	v_mul_f32_e32 v175, v172, v139
	v_mul_f32_e32 v48, v174, v48
	v_mul_f32_e32 v174, v172, v128
	v_mul_f32_e32 v49, v175, v49
	v_mul_f32_e32 v175, v172, v129
	v_mul_f32_e32 v44, v174, v44
	v_mul_f32_e32 v45, v175, v45
	v_max_f32_e32 v48, 0, v48
	v_max_f32_e32 v44, 0, v44
	v_max_f32_e32 v49, 0, v49
	v_max_f32_e32 v45, 0, v45
	v_mul_f32_e32 v48, v48, v48
	v_mul_f32_e32 v44, v44, v44
	v_mul_f32_e32 v49, v49, v49
	v_mul_f32_e32 v45, v45, v45
	v_max_f32_e32 v174, v48, v44
	v_max_f32_e32 v175, v49, v45
	v_max3_f32 v173, v173, v174, v175
	v_mul_f32_e32 v174, v172, v118
	v_mul_f32_e32 v175, v172, v119
	v_mul_f32_e32 v38, v174, v38
	v_mul_f32_e32 v174, v172, v114
	v_mul_f32_e32 v39, v175, v39
	v_mul_f32_e32 v175, v172, v115
	v_mul_f32_e32 v34, v174, v34
	v_mul_f32_e32 v35, v175, v35
	v_max_f32_e32 v38, 0, v38
	v_max_f32_e32 v34, 0, v34
	v_max_f32_e32 v39, 0, v39
	v_max_f32_e32 v35, 0, v35
	v_mul_f32_e32 v38, v38, v38
	v_mul_f32_e32 v34, v34, v34
	v_mul_f32_e32 v39, v39, v39
	v_mul_f32_e32 v35, v35, v35
	v_max_f32_e32 v174, v38, v34
	v_max_f32_e32 v175, v39, v35
	v_max3_f32 v173, v173, v174, v175
	v_mul_f32_e32 v174, v172, v120
	v_mul_f32_e32 v40, v174, v40
	v_mul_f32_e32 v174, v172, v116
	v_mul_f32_e32 v175, v172, v121
	v_mul_f32_e32 v172, v172, v117
	v_mul_f32_e32 v36, v174, v36
	v_mul_f32_e32 v41, v175, v41
	v_mul_f32_e32 v37, v172, v37
	v_max_f32_e32 v40, 0, v40
	v_max_f32_e32 v36, 0, v36
	v_max_f32_e32 v41, 0, v41
	v_max_f32_e32 v37, 0, v37
	v_mul_f32_e32 v40, v40, v40
	v_mul_f32_e32 v36, v36, v36
	v_mul_f32_e32 v172, v41, v41
	v_mul_f32_e32 v41, v37, v37
	v_max_f32_e32 v174, v40, v36
	v_max_f32_e32 v37, v172, v41
	v_max3_f32 v37, v173, v174, v37
	ds_bpermute_b32 v173, v169, v37
	s_waitcnt lgkmcnt(0)
	v_max_f32_e32 v173, v173, v173
	v_max_f32_e32 v37, v37, v173
	ds_bpermute_b32 v173, v170, v37
	s_and_saveexec_b64 s[42:43], vcc
	s_cbranch_execz .LBB0_1351
	s_waitcnt lgkmcnt(0)
	v_max_f32_e32 v173, v173, v173
	v_max_f32_e32 v37, v37, v37
	v_max_f32_e32 v37, v37, v173
	ds_write_b32 v168, v37 offset:576
;     __device__ __forceinline__ void operator()(f32x4 (&acc)[2][2][4][2], const Unit& u, int wr, int wc, int fr_in, int fq_in, int wid, LAS unsigned char* lds) const {
;     ...
;         for (int ai = 0; ai < 2; ++ai)
; #pragma unroll
;             for (int m = 0; m < 4; ++m) {
;                 const float s = sv[ai * 4 + m];
;                 float mx = 0.f;
; #pragma unroll
;                 for (int bj = 0; bj < 2; ++bj) {
;                     const v4i_t i0 = __builtin_bit_cast(v4i_t, acc[ai][bj][m][0]), i1 = __builtin_bit_cast(v4i_t, acc[ai][bj][m][1]);
;                     const u32x4 c0_ = cv[bj * 2], c1_ = cv[bj * 2 + 1];
;                     f32x4 v0, v1;
; #pragma unroll
;                     for (int j = 0; j < 4; ++j) { const float a = fmaxf((float)i0[j] * (s * __uint_as_float(c0_[j])), 0.f), b = fmaxf((float)i1[j] * (s * __uint_as_float(c1_[j])), 0.f); v0[j] = a * a; v1[j] = b * b; mx = fmaxf(mx, fmaxf(v0[j], v1[j])); }
;                     acc[ai][bj][m][0] = v0; acc[ai][bj][m][1] = v1;
;                 }
;                 mx = fmaxf(mx, __shfl_xor(mx, 16)); mx = fmaxf(mx, __shfl_xor(mx, 32));
;                 if (fq == 0) lmx[wc * 256 + wr * 64 + ai * HALF + m * 16 + fr] = mx;
.LBB0_1351:
	s_or_b64 exec, exec, s[42:43]
	s_waitcnt lgkmcnt(0)
	v_mul_f32_e32 v173, 0x3c010204, v171
	v_mul_f32_e32 v37, v173, v136
	v_mul_f32_e32 v171, v173, v137
	v_mul_f32_e32 v30, v37, v30
	v_mul_f32_e32 v37, v173, v126
	v_mul_f32_e32 v31, v171, v31
	v_mul_f32_e32 v171, v173, v127
	v_mul_f32_e32 v26, v37, v26
	v_mul_f32_e32 v27, v171, v27
	v_max_f32_e32 v30, 0, v30
	v_max_f32_e32 v26, 0, v26
	v_max_f32_e32 v31, 0, v31
	v_max_f32_e32 v27, 0, v27
	v_mul_f32_e32 v30, v30, v30
	v_mul_f32_e32 v26, v26, v26
	v_mul_f32_e32 v31, v31, v31
	v_mul_f32_e32 v27, v27, v27
	v_max_f32_e32 v37, v30, v26
	v_max_f32_e32 v171, v31, v27
	v_max3_f32 v37, v37, 0, v171
	v_mul_f32_e32 v171, v173, v138
	v_mul_f32_e32 v174, v173, v139
	v_mul_f32_e32 v32, v171, v32
	v_mul_f32_e32 v171, v173, v128
	v_mul_f32_e32 v33, v174, v33
	v_mul_f32_e32 v174, v173, v129
	v_mul_f32_e32 v28, v171, v28
	v_mul_f32_e32 v29, v174, v29
	v_max_f32_e32 v32, 0, v32
	v_max_f32_e32 v28, 0, v28
	v_max_f32_e32 v33, 0, v33
	v_max_f32_e32 v29, 0, v29
	v_mul_f32_e32 v32, v32, v32
	v_mul_f32_e32 v28, v28, v28
	v_mul_f32_e32 v33, v33, v33
	v_mul_f32_e32 v29, v29, v29
	v_max_f32_e32 v171, v32, v28
	v_max_f32_e32 v174, v33, v29
	v_max3_f32 v174, v37, v171, v174
	v_mul_f32_e32 v37, v173, v118
	v_mul_f32_e32 v22, v37, v22
	v_mul_f32_e32 v37, v173, v114
	v_mul_f32_e32 v18, v37, v18
	v_max_f32_e32 v22, 0, v22
	v_max_f32_e32 v18, 0, v18
	v_mul_f32_e32 v37, v22, v22
	v_mul_f32_e32 v22, v18, v18
	v_cvt_f32_i32_e32 v18, v23
	v_mul_f32_e32 v23, v173, v119
	v_mul_f32_e32 v18, v23, v18
	v_mul_f32_e32 v23, v173, v115
	v_mul_f32_e32 v19, v23, v19
	v_max_f32_e32 v19, 0, v19
	v_mul_f32_e32 v23, v19, v19
	v_cvt_f32_i32_e32 v19, v24
	v_mul_f32_e32 v24, v173, v120
	v_max_f32_e32 v18, 0, v18
	v_mul_f32_e32 v19, v24, v19
	v_max_f32_e32 v19, 0, v19
	v_mul_f32_e32 v24, v173, v116
	v_mul_f32_e32 v20, v24, v20
	v_mul_f32_e32 v24, v19, v19
	v_cvt_f32_i32_e32 v19, v25
	v_mul_f32_e32 v171, v18, v18
	v_max_f32_e32 v175, v37, v22
	v_max_f32_e32 v18, v171, v23
	v_max3_f32 v18, v174, v175, v18
	v_mul_f32_e32 v174, v173, v121
	v_mul_f32_e32 v173, v173, v117
	v_mul_f32_e32 v19, v174, v19
	v_mul_f32_e32 v21, v173, v21
	v_max_f32_e32 v20, 0, v20
	v_max_f32_e32 v19, 0, v19
	v_max_f32_e32 v21, 0, v21
	v_mul_f32_e32 v20, v20, v20
	v_mul_f32_e32 v174, v19, v19
	v_mul_f32_e32 v173, v21, v21
	v_max_f32_e32 v25, v24, v20
	v_max_f32_e32 v19, v174, v173
	v_max3_f32 v18, v18, v25, v19
	ds_bpermute_b32 v19, v169, v18
	s_waitcnt lgkmcnt(0)
	v_max_f32_e32 v19, v19, v19
	v_max_f32_e32 v18, v18, v19
	ds_bpermute_b32 v19, v170, v18
	s_and_saveexec_b64 s[42:43], vcc
	s_cbranch_execz .LBB0_1353
	s_waitcnt lgkmcnt(0)
	v_max_f32_e32 v19, v19, v19
	v_max_f32_e32 v18, v18, v18
	v_max_f32_e32 v18, v18, v19
	ds_write_b32 v168, v18 offset:640
.LBB0_1353:
	s_or_b64 exec, exec, s[42:43]
	v_mul_f32_e32 v167, 0x3c010204, v167
	v_mul_f32_e32 v18, v167, v136
	v_mul_f32_e32 v14, v18, v14
	v_mul_f32_e32 v18, v167, v126
	v_mul_f32_e32 v10, v18, v10
	v_max_f32_e32 v14, 0, v14
	v_max_f32_e32 v10, 0, v10
	v_mul_f32_e32 v18, v14, v14
	v_mul_f32_e32 v14, v10, v10
	v_cvt_f32_i32_e32 v10, v15
	v_mul_f32_e32 v15, v167, v137
	v_mul_f32_e32 v10, v15, v10
	v_mul_f32_e32 v15, v167, v127
	v_mul_f32_e32 v11, v15, v11
	v_max_f32_e32 v11, 0, v11
	v_mul_f32_e32 v15, v11, v11
	v_cvt_f32_i32_e32 v11, v16
	v_mul_f32_e32 v16, v167, v138
	v_max_f32_e32 v10, 0, v10
	v_mul_f32_e32 v11, v16, v11
	v_max_f32_e32 v11, 0, v11
	v_mul_f32_e32 v16, v167, v128
	v_mul_f32_e32 v12, v16, v12
	v_mul_f32_e32 v16, v11, v11
	v_cvt_f32_i32_e32 v11, v17
	v_mul_f32_e32 v17, v167, v139
	s_waitcnt lgkmcnt(0)
	v_mul_f32_e32 v19, v10, v10
	v_max_f32_e32 v12, 0, v12
	v_mul_f32_e32 v11, v17, v11
	v_mul_f32_e32 v17, v167, v129
	v_mul_f32_e32 v13, v17, v13
	v_max_f32_e32 v11, 0, v11
	v_max_f32_e32 v13, 0, v13
	v_max_f32_e32 v21, v18, v14
	v_max_f32_e32 v10, v19, v15
	v_mul_f32_e32 v12, v12, v12
	v_mul_f32_e32 v17, v11, v11
	v_mul_f32_e32 v13, v13, v13
	v_max3_f32 v10, v21, 0, v10
	v_max_f32_e32 v21, v16, v12
	v_max_f32_e32 v11, v17, v13
	v_max3_f32 v10, v10, v21, v11
	v_mul_f32_e32 v11, v167, v118
	v_mul_f32_e32 v6, v11, v6
	v_mul_f32_e32 v11, v167, v114
	v_mul_f32_e32 v2, v11, v2
	v_max_f32_e32 v2, 0, v2
	v_mul_f32_e32 v21, v2, v2
	v_cvt_f32_i32_e32 v2, v7
	v_mul_f32_e32 v7, v167, v119
	v_max_f32_e32 v6, 0, v6
	v_mul_f32_e32 v2, v7, v2
	v_mul_f32_e32 v7, v167, v115
	v_mul_f32_e32 v3, v7, v3
	v_max_f32_e32 v3, 0, v3
	v_max_f32_e32 v2, 0, v2
	v_mul_f32_e32 v114, v3, v3
	v_cvt_f32_i32_e32 v3, v8
	v_mul_f32_e32 v25, v6, v6
	v_mul_f32_e32 v115, v2, v2
	v_max_f32_e32 v6, v25, v21
	v_max_f32_e32 v2, v115, v114
	v_max3_f32 v2, v10, v6, v2
	v_mul_f32_e32 v6, v167, v120
	v_mul_f32_e32 v3, v6, v3
	v_max_f32_e32 v3, 0, v3
	v_mul_f32_e32 v118, v3, v3
	v_cvt_f32_i32_e32 v3, v9
	v_mul_f32_e32 v6, v167, v116
	v_mul_f32_e32 v4, v6, v4
	v_mul_f32_e32 v6, v167, v121
	v_mul_f32_e32 v3, v6, v3
	v_mul_f32_e32 v6, v167, v117
	v_mul_f32_e32 v5, v6, v5
	v_max_f32_e32 v4, 0, v4
	v_max_f32_e32 v3, 0, v3
	v_max_f32_e32 v5, 0, v5
	v_mul_f32_e32 v116, v4, v4
	v_mul_f32_e32 v119, v3, v3
	v_mul_f32_e32 v117, v5, v5
	v_max_f32_e32 v4, v118, v116
	v_max_f32_e32 v3, v119, v117
	v_max3_f32 v2, v2, v4, v3
	ds_bpermute_b32 v3, v169, v2
	s_waitcnt lgkmcnt(0)
	v_max_f32_e32 v3, v3, v3
	v_max_f32_e32 v2, v2, v3
	ds_bpermute_b32 v3, v170, v2
	s_and_saveexec_b64 s[42:43], vcc
	s_cbranch_execz .LBB0_1355
	s_waitcnt lgkmcnt(0)
	v_max_f32_e32 v3, v3, v3
	v_max_f32_e32 v2, v2, v2
	v_max_f32_e32 v2, v2, v3
	ds_write_b32 v168, v2 offset:704
